# v50 + gmlp_sample_item: the eight row-sum loads issued as one batch, and a touch prefetch of the eight gating rows before the row-scale step (later per-step loads hit cache)
# baseline (speedup 1.0000x reference)
.LBB0_600:
	v_lshlrev_b32_e32 v150, 2, v84
	v_readlane_b32 s36, v255, 11
	v_and_b32_e32 v150, 0xfc, v150
	v_readlane_b32 s38, v255, 13
	v_readlane_b32 s39, v255, 14
	v_or_b32_e32 v150, s36, v150
	v_readlane_b32 s40, v255, 15
	v_readlane_b32 s41, v255, 16
	v_lshlrev_b32_e32 v150, 1, v150
	v_readlane_b32 s42, v255, 17
	v_readlane_b32 s43, v255, 18
	v_readlane_b32 s44, v255, 19
	v_readlane_b32 s45, v255, 20
	v_readlane_b32 s46, v255, 21
	v_readlane_b32 s47, v255, 22
	v_readlane_b32 s48, v255, 23
	v_readlane_b32 s49, v255, 24
	v_readlane_b32 s50, v255, 25
	v_readlane_b32 s51, v255, 26
	v_readlane_b32 s36, v255, 27
	v_readlane_b32 s37, v255, 28
	s_nop 4
	global_load_dwordx2 v[152:153], v150, s[38:39]
	global_load_dwordx2 v[154:155], v150, s[40:41]
	global_load_dwordx2 v[156:157], v150, s[42:43]
	global_load_dwordx2 v[158:159], v150, s[44:45]
	global_load_dwordx2 v[160:161], v150, s[46:47]
	global_load_dwordx2 v[162:163], v150, s[48:49]
	global_load_dwordx2 v[164:165], v150, s[50:51]
	global_load_dwordx2 v[166:167], v150, s[36:37]
	v_cmp_gt_i32_e32 vcc, 8, v119
	s_and_saveexec_b64 s[2:3], vcc
	s_cbranch_execz .LBB0_602
	v_readlane_b32 s0, v255, 34
	v_readlane_b32 s1, v255, 35
	v_lshl_add_u32 v0, v119, 2, 0
	v_add_u32_e32 v2, s0, v119
	v_ashrrev_i32_e32 v3, 31, v2
	v_lshlrev_b64 v[2:3], 7, v[2:3]
	v_lshl_add_u64 v[18:19], s[74:75], 0, v[2:3]
	global_load_dwordx4 v[2:5], v[18:19], off offset:48
	global_load_dwordx4 v[6:9], v[18:19], off offset:32
	global_load_dwordx4 v[10:13], v[18:19], off
	global_load_dwordx4 v[14:17], v[18:19], off offset:16
	global_load_dwordx4 v[132:135], v[18:19], off offset:112
	global_load_dwordx4 v[136:139], v[18:19], off offset:96
	global_load_dwordx4 v[140:143], v[18:19], off offset:80
	global_load_dwordx4 v[144:147], v[18:19], off offset:64
	s_waitcnt vmcnt(7)
	v_add_f32_e32 v24, v2, v3
	v_add_f32_e32 v26, v4, v5
	s_waitcnt vmcnt(5)
	v_mov_b32_e32 v20, v10
	s_waitcnt vmcnt(4)
	v_mov_b32_e32 v21, v14
	v_mov_b32_e32 v14, v11
	v_pk_add_f32 v[10:11], v[20:21], v[14:15]
	v_mov_b32_e32 v14, v12
	v_mov_b32_e32 v15, v16
	v_mov_b32_e32 v16, v13
	v_pk_add_f32 v[12:13], v[14:15], v[16:17]
	s_nop 0
	v_pk_add_f32 v[10:11], v[10:11], v[12:13]
	s_nop 0
	v_add_f32_e32 v10, 0, v10
	v_add_f32_e32 v20, v10, v11
	v_mov_b32_e32 v10, v7
	v_mov_b32_e32 v11, v8
	v_mov_b32_e32 v7, v9
	v_pk_add_f32 v[6:7], v[10:11], v[6:7]
	s_nop 0
	v_pk_add_f32 v[22:23], v[6:7], v[6:7] op_sel:[0,1] op_sel_hi:[1,0]
	s_waitcnt vmcnt(2)
	v_add_f32_e32 v136, v136, v137
	v_add_f32_e32 v138, v138, v139
	s_waitcnt vmcnt(0)
	v_mov_b32_e32 v21, v144
	v_mov_b32_e32 v23, v145
	v_mov_b32_e32 v25, v146
	v_mov_b32_e32 v27, v147
	v_pk_add_f32 v[144:145], v[20:21], v[22:23]
	v_pk_add_f32 v[146:147], v[24:25], v[26:27]
	v_mov_b32_e32 v137, v134
	v_pk_add_f32 v[144:145], v[144:145], v[146:147]
	v_mov_b32_e32 v146, v141
	v_mov_b32_e32 v147, v142
	v_mov_b32_e32 v141, v143
	v_pk_add_f32 v[140:141], v[146:147], v[140:141]
	v_pk_add_f32 v[144:145], v[144:145], v[144:145] op_sel:[0,1] op_sel_hi:[1,0]
	v_pk_add_f32 v[140:141], v[140:141], v[140:141] op_sel:[0,1] op_sel_hi:[1,0]
	v_mov_b32_e32 v145, v132
	v_mov_b32_e32 v141, v133
	v_mov_b32_e32 v139, v135
	v_pk_add_f32 v[132:133], v[144:145], v[140:141]
	v_pk_add_f32 v[134:135], v[136:137], v[138:139]
	s_nop 0
	v_pk_add_f32 v[132:133], v[132:133], v[134:135]
	s_nop 0
	v_add_f32_e32 v132, v132, v133
	v_fmamk_f32 v132, v132, 0x3a000000, v211
	v_cmp_gt_f32_e32 vcc, s94, v132
	v_mul_f32_e32 v133, 0x4f800000, v132
	s_nop 0
	v_cndmask_b32_e32 v132, v132, v133, vcc
	v_sqrt_f32_e32 v133, v132
	s_nop 0
	v_add_u32_e32 v134, -1, v133
	v_fma_f32 v135, -v134, v133, v132
	v_cmp_ge_f32_e64 s[0:1], 0, v135
	v_add_u32_e32 v135, 1, v133
	s_nop 0
	v_cndmask_b32_e64 v134, v133, v134, s[0:1]
	v_fma_f32 v133, -v135, v133, v132
	v_cmp_lt_f32_e64 s[0:1], 0, v133
	s_nop 1
	v_cndmask_b32_e64 v133, v134, v135, s[0:1]
	v_mul_f32_e32 v134, 0x37800000, v133
	v_cndmask_b32_e32 v133, v133, v134, vcc
	v_cmp_class_f32_e32 vcc, v132, v212
	s_nop 1
	v_cndmask_b32_e32 v132, v133, v132, vcc
	v_div_scale_f32 v133, s[0:1], v132, v132, 1.0
	v_rcp_f32_e32 v134, v133
	s_nop 0
	v_fma_f32 v135, -v133, v134, 1.0
	v_fmac_f32_e32 v134, v135, v134
	v_div_scale_f32 v135, vcc, 1.0, v132, 1.0
	v_mul_f32_e32 v136, v135, v134
	v_fma_f32 v137, -v133, v136, v135
	v_fmac_f32_e32 v136, v137, v134
	v_fma_f32 v133, -v133, v136, v135
	v_div_fmas_f32 v133, v133, v134, v136
	v_div_fixup_f32 v132, v133, v132, 1.0
	ds_write_b32 v0, v132
